# grid barrier: waiting workgroups issue their L1 invalidate when they start waiting; XCD leader completes its invalidate before releasing locals
# speedup vs baseline: 1.0100x; 1.0066x over previous
; __device__ __forceinline__ unsigned xb_ld(unsigned* p)              { return __hip_atomic_load(p, __ATOMIC_RELAXED, __HIP_MEMORY_SCOPE_AGENT); }
; __device__ __forceinline__ unsigned xb_add(unsigned* p, unsigned v) { return __hip_atomic_fetch_add(p, v, __ATOMIC_RELAXED, __HIP_MEMORY_SCOPE_AGENT); }
; #define XB_SPIN(cond, bar) do { unsigned _sp = 0; while (cond) { __builtin_amdgcn_s_sleep(1); \
;     if ((++_sp & 255u) == 0u) { if (xb_ld(&(bar)[XB_TMO])) break; if (_sp > XB_SPIN_CAP) { atomicAdd(&(bar)[XB_TMO], 1u); break; } } } } while (0)
; __device__ __forceinline__ void xcd_barrier(const XcdBarrier& b, int wave_id) {
;     ...
;         const unsigned old = xb_add(&bar[XB_XSUB(b.x)], 1u);
;         const unsigned gen = old / nloc;
;         if (old + 1u == (gen + 1u) * nloc) {
;             __builtin_amdgcn_fence(__ATOMIC_RELEASE, "agent");
;             asm volatile("s_waitcnt vmcnt(0)" ::: "memory");
;             const unsigned og = xb_add(&bar[XB_TOP], 1u);
;             const unsigned tg = og / nx;
;             if (og + 1u == (tg + 1u) * nx) xb_add(&bar[XB_TOPGEN], 1u);
;             else XB_SPIN(xb_ld(&bar[XB_TOPGEN]) == tg, bar);
;             __builtin_amdgcn_fence(__ATOMIC_ACQUIRE, "agent");
;             xb_add(&bar[XB_XGEN(b.x)], 1u);
;             asm volatile("s_waitcnt vmcnt(0)" ::: "memory");
;         } else {
;             XB_SPIN(xb_ld(&bar[XB_XGEN(b.x)]) == gen, bar);
;             __builtin_amdgcn_fence(__ATOMIC_ACQUIRE, "agent");
;             asm volatile("s_waitcnt vmcnt(0)" ::: "memory");
;         }
.LBB0_65:
	s_or_b64 exec, exec, s[18:19]
	v_cvt_f32_u32_e32 v4, v2
	s_waitcnt vmcnt(0)
	v_readfirstlane_b32 s8, v3
	v_sub_u32_e32 v3, 0, v2
	v_rcp_iflag_f32_e32 v4, v4
	v_add_u32_e32 v5, s8, v1
	v_mul_f32_e32 v4, 0x4f7ffffe, v4
	v_cvt_u32_f32_e32 v4, v4
	v_mul_lo_u32 v1, v3, v4
	v_mul_hi_u32 v1, v4, v1
	v_add_u32_e32 v1, v4, v1
	v_mul_hi_u32 v1, v5, v1
	v_mul_lo_u32 v3, v1, v2
	v_sub_u32_e32 v3, v5, v3
	v_add_u32_e32 v4, 1, v1
	v_cmp_ge_u32_e32 vcc, v3, v2
	s_nop 1
	v_cndmask_b32_e32 v1, v1, v4, vcc
	v_sub_u32_e32 v4, v3, v2
	v_cndmask_b32_e32 v3, v3, v4, vcc
	v_add_u32_e32 v4, 1, v1
	v_cmp_ge_u32_e32 vcc, v3, v2
	v_add_u32_e32 v3, 1, v5
	s_nop 0
	v_cndmask_b32_e32 v1, v1, v4, vcc
	v_mul_lo_u32 v4, v2, v1
	v_add_u32_e32 v2, v4, v2
	v_cmp_ne_u32_e32 vcc, v3, v2
	s_and_saveexec_b64 s[8:9], vcc
	s_xor_b64 s[8:9], exec, s[8:9]
	s_cbranch_execz .LBB0_79
	s_waitcnt lgkmcnt(0)
	buffer_inv sc1
	v_mov_b32_e32 v0, 0x2000
	global_load_dword v0, v0, s[6:7] offset:1024 sc1
	s_add_u32 s22, s6, 0x2400
	s_addc_u32 s23, s7, 0
	s_waitcnt vmcnt(0)
	v_cmp_eq_u32_e32 vcc, v0, v1
	s_and_saveexec_b64 s[18:19], vcc
	s_cbranch_execz .LBB0_78
	s_add_u32 s20, s14, 0xff40200
	s_addc_u32 s21, s15, 0
	s_mov_b32 s26, 1
	s_mov_b64 s[30:31], 0
	v_mov_b32_e32 v0, 0
	s_branch .LBB0_69

; __device__ __forceinline__ unsigned xb_ld(unsigned* p)              { return __hip_atomic_load(p, __ATOMIC_RELAXED, __HIP_MEMORY_SCOPE_AGENT); }
; #define XB_SPIN(cond, bar) do { unsigned _sp = 0; while (cond) { __builtin_amdgcn_s_sleep(1); \
;     if ((++_sp & 255u) == 0u) { if (xb_ld(&(bar)[XB_TMO])) break; if (_sp > XB_SPIN_CAP) { atomicAdd(&(bar)[XB_TMO], 1u); break; } } } } while (0)
; __device__ __forceinline__ void xcd_barrier(const XcdBarrier& b, int wave_id) {
;     ...
;             XB_SPIN(xb_ld(&bar[XB_XGEN(b.x)]) == gen, bar);
;             __builtin_amdgcn_fence(__ATOMIC_ACQUIRE, "agent");
;             asm volatile("s_waitcnt vmcnt(0)" ::: "memory");
.LBB0_78:
	s_or_b64 exec, exec, s[18:19]
	s_waitcnt vmcnt(0)
	s_nop 0
	s_waitcnt vmcnt(0)

; __device__ __forceinline__ unsigned xb_add(unsigned* p, unsigned v) { return __hip_atomic_fetch_add(p, v, __ATOMIC_RELAXED, __HIP_MEMORY_SCOPE_AGENT); }
; __device__ __forceinline__ void xcd_barrier(const XcdBarrier& b, int wave_id) {
;     ...
;             __builtin_amdgcn_fence(__ATOMIC_ACQUIRE, "agent");
;             xb_add(&bar[XB_XGEN(b.x)], 1u);
;             asm volatile("s_waitcnt vmcnt(0)" ::: "memory");
.LBB0_96:
	s_or_b64 exec, exec, s[8:9]
	s_mov_b64 s[8:9], exec
	v_mbcnt_lo_u32_b32 v0, s8, 0
	v_mbcnt_hi_u32_b32 v0, s9, v0
	v_cmp_eq_u32_e32 vcc, 0, v0
	s_waitcnt vmcnt(0)
	buffer_inv sc1
	s_waitcnt vmcnt(0)
	s_and_saveexec_b64 s[18:19], vcc
	s_cbranch_execz .LBB0_98
	s_bcnt1_i32_b64 s8, s[8:9]
	v_mov_b32_e32 v0, 0x2000
	v_mov_b32_e32 v1, s8
	global_atomic_add v0, v1, s[6:7] offset:1024

; __device__ __forceinline__ unsigned xb_ld(unsigned* p)              { return __hip_atomic_load(p, __ATOMIC_RELAXED, __HIP_MEMORY_SCOPE_AGENT); }
; __device__ __forceinline__ unsigned xb_add(unsigned* p, unsigned v) { return __hip_atomic_fetch_add(p, v, __ATOMIC_RELAXED, __HIP_MEMORY_SCOPE_AGENT); }
; #define XB_SPIN(cond, bar) do { unsigned _sp = 0; while (cond) { __builtin_amdgcn_s_sleep(1); \
;     if ((++_sp & 255u) == 0u) { if (xb_ld(&(bar)[XB_TMO])) break; if (_sp > XB_SPIN_CAP) { atomicAdd(&(bar)[XB_TMO], 1u); break; } } } } while (0)
; __device__ __forceinline__ void xcd_barrier(const XcdBarrier& b, int wave_id) {
;     ...
;         const unsigned old = xb_add(&bar[XB_XSUB(b.x)], 1u);
;         const unsigned gen = old / nloc;
;         if (old + 1u == (gen + 1u) * nloc) {
;             __builtin_amdgcn_fence(__ATOMIC_RELEASE, "agent");
;             asm volatile("s_waitcnt vmcnt(0)" ::: "memory");
;             const unsigned og = xb_add(&bar[XB_TOP], 1u);
;             const unsigned tg = og / nx;
;             if (og + 1u == (tg + 1u) * nx) xb_add(&bar[XB_TOPGEN], 1u);
;             else XB_SPIN(xb_ld(&bar[XB_TOPGEN]) == tg, bar);
;             __builtin_amdgcn_fence(__ATOMIC_ACQUIRE, "agent");
;             xb_add(&bar[XB_XGEN(b.x)], 1u);
;             asm volatile("s_waitcnt vmcnt(0)" ::: "memory");
;         } else {
;             XB_SPIN(xb_ld(&bar[XB_XGEN(b.x)]) == gen, bar);
;             __builtin_amdgcn_fence(__ATOMIC_ACQUIRE, "agent");
;             asm volatile("s_waitcnt vmcnt(0)" ::: "memory");
;         }
.LBB0_225:
	s_or_b64 exec, exec, s[10:11]
	v_cvt_f32_u32_e32 v4, v2
	s_waitcnt vmcnt(0)
	v_readfirstlane_b32 s8, v3
	v_sub_u32_e32 v3, 0, v2
	v_rcp_iflag_f32_e32 v4, v4
	v_add_u32_e32 v5, s8, v1
	v_mul_f32_e32 v4, 0x4f7ffffe, v4
	v_cvt_u32_f32_e32 v4, v4
	v_mul_lo_u32 v1, v3, v4
	v_mul_hi_u32 v1, v4, v1
	v_add_u32_e32 v1, v4, v1
	v_mul_hi_u32 v1, v5, v1
	v_mul_lo_u32 v3, v1, v2
	v_sub_u32_e32 v3, v5, v3
	v_add_u32_e32 v4, 1, v1
	v_cmp_ge_u32_e32 vcc, v3, v2
	s_nop 1
	v_cndmask_b32_e32 v1, v1, v4, vcc
	v_sub_u32_e32 v4, v3, v2
	v_cndmask_b32_e32 v3, v3, v4, vcc
	v_add_u32_e32 v4, 1, v1
	v_cmp_ge_u32_e32 vcc, v3, v2
	v_add_u32_e32 v3, 1, v5
	s_nop 0
	v_cndmask_b32_e32 v1, v1, v4, vcc
	v_mul_lo_u32 v4, v2, v1
	v_add_u32_e32 v2, v4, v2
	v_cmp_ne_u32_e32 vcc, v3, v2
	s_and_saveexec_b64 s[8:9], vcc
	s_xor_b64 s[8:9], exec, s[8:9]
	s_cbranch_execz .LBB0_239
	s_waitcnt lgkmcnt(0)
	buffer_inv sc1
	v_mov_b32_e32 v0, 0x2000
	global_load_dword v0, v0, s[6:7] offset:1024 sc1
	s_add_u32 s22, s6, 0x2400
	s_addc_u32 s23, s7, 0
	s_waitcnt vmcnt(0)
	v_cmp_eq_u32_e32 vcc, v0, v1
	s_and_saveexec_b64 s[10:11], vcc
	s_cbranch_execz .LBB0_238
	s_add_u32 s20, s14, 0xff40200
	s_addc_u32 s21, s15, 0
	s_mov_b32 s26, 1
	s_mov_b64 s[44:45], 0
	v_mov_b32_e32 v0, 0
	s_branch .LBB0_229

; __device__ __forceinline__ unsigned xb_ld(unsigned* p)              { return __hip_atomic_load(p, __ATOMIC_RELAXED, __HIP_MEMORY_SCOPE_AGENT); }
; #define XB_SPIN(cond, bar) do { unsigned _sp = 0; while (cond) { __builtin_amdgcn_s_sleep(1); \
;     if ((++_sp & 255u) == 0u) { if (xb_ld(&(bar)[XB_TMO])) break; if (_sp > XB_SPIN_CAP) { atomicAdd(&(bar)[XB_TMO], 1u); break; } } } } while (0)
; __device__ __forceinline__ void xcd_barrier(const XcdBarrier& b, int wave_id) {
;     ...
;             XB_SPIN(xb_ld(&bar[XB_XGEN(b.x)]) == gen, bar);
;             __builtin_amdgcn_fence(__ATOMIC_ACQUIRE, "agent");
;             asm volatile("s_waitcnt vmcnt(0)" ::: "memory");
.LBB0_238:
	s_or_b64 exec, exec, s[10:11]
	s_waitcnt vmcnt(0)
	s_nop 0
	s_waitcnt vmcnt(0)

; __device__ __forceinline__ unsigned xb_add(unsigned* p, unsigned v) { return __hip_atomic_fetch_add(p, v, __ATOMIC_RELAXED, __HIP_MEMORY_SCOPE_AGENT); }
; __device__ __forceinline__ void xcd_barrier(const XcdBarrier& b, int wave_id) {
;     ...
;             __builtin_amdgcn_fence(__ATOMIC_ACQUIRE, "agent");
;             xb_add(&bar[XB_XGEN(b.x)], 1u);
;             asm volatile("s_waitcnt vmcnt(0)" ::: "memory");
.LBB0_256:
	s_or_b64 exec, exec, s[8:9]
	s_mov_b64 s[8:9], exec
	v_mbcnt_lo_u32_b32 v0, s8, 0
	v_mbcnt_hi_u32_b32 v0, s9, v0
	v_cmp_eq_u32_e32 vcc, 0, v0
	s_waitcnt vmcnt(0)
	buffer_inv sc1
	s_waitcnt vmcnt(0)
	s_and_saveexec_b64 s[10:11], vcc
	s_cbranch_execz .LBB0_258
	s_bcnt1_i32_b64 s8, s[8:9]
	v_mov_b32_e32 v0, 0x2000
	v_mov_b32_e32 v1, s8
	global_atomic_add v0, v1, s[6:7] offset:1024

; __device__ __forceinline__ unsigned xb_ld(unsigned* p)              { return __hip_atomic_load(p, __ATOMIC_RELAXED, __HIP_MEMORY_SCOPE_AGENT); }
; __device__ __forceinline__ unsigned xb_add(unsigned* p, unsigned v) { return __hip_atomic_fetch_add(p, v, __ATOMIC_RELAXED, __HIP_MEMORY_SCOPE_AGENT); }
; #define XB_SPIN(cond, bar) do { unsigned _sp = 0; while (cond) { __builtin_amdgcn_s_sleep(1); \
;     if ((++_sp & 255u) == 0u) { if (xb_ld(&(bar)[XB_TMO])) break; if (_sp > XB_SPIN_CAP) { atomicAdd(&(bar)[XB_TMO], 1u); break; } } } } while (0)
; __device__ __forceinline__ void xcd_barrier(const XcdBarrier& b, int wave_id) {
;     ...
;         const unsigned old = xb_add(&bar[XB_XSUB(b.x)], 1u);
;         const unsigned gen = old / nloc;
;         if (old + 1u == (gen + 1u) * nloc) {
;             __builtin_amdgcn_fence(__ATOMIC_RELEASE, "agent");
;             asm volatile("s_waitcnt vmcnt(0)" ::: "memory");
;             const unsigned og = xb_add(&bar[XB_TOP], 1u);
;             const unsigned tg = og / nx;
;             if (og + 1u == (tg + 1u) * nx) xb_add(&bar[XB_TOPGEN], 1u);
;             else XB_SPIN(xb_ld(&bar[XB_TOPGEN]) == tg, bar);
;             __builtin_amdgcn_fence(__ATOMIC_ACQUIRE, "agent");
;             xb_add(&bar[XB_XGEN(b.x)], 1u);
;             asm volatile("s_waitcnt vmcnt(0)" ::: "memory");
;         } else {
;             XB_SPIN(xb_ld(&bar[XB_XGEN(b.x)]) == gen, bar);
;             __builtin_amdgcn_fence(__ATOMIC_ACQUIRE, "agent");
;             asm volatile("s_waitcnt vmcnt(0)" ::: "memory");
;         }
.LBB0_387:
	s_or_b64 exec, exec, s[22:23]
	v_cvt_f32_u32_e32 v4, v2
	s_waitcnt vmcnt(0)
	v_readfirstlane_b32 s6, v3
	v_sub_u32_e32 v3, 0, v2
	v_rcp_iflag_f32_e32 v4, v4
	v_add_u32_e32 v5, s6, v1
	v_mul_f32_e32 v4, 0x4f7ffffe, v4
	v_cvt_u32_f32_e32 v4, v4
	v_mul_lo_u32 v1, v3, v4
	v_mul_hi_u32 v1, v4, v1
	v_add_u32_e32 v1, v4, v1
	v_mul_hi_u32 v1, v5, v1
	v_mul_lo_u32 v3, v1, v2
	v_sub_u32_e32 v3, v5, v3
	v_add_u32_e32 v4, 1, v1
	v_cmp_ge_u32_e32 vcc, v3, v2
	s_nop 1
	v_cndmask_b32_e32 v1, v1, v4, vcc
	v_sub_u32_e32 v4, v3, v2
	v_cndmask_b32_e32 v3, v3, v4, vcc
	v_add_u32_e32 v4, 1, v1
	v_cmp_ge_u32_e32 vcc, v3, v2
	v_add_u32_e32 v3, 1, v5
	s_nop 0
	v_cndmask_b32_e32 v1, v1, v4, vcc
	v_mul_lo_u32 v4, v2, v1
	v_add_u32_e32 v2, v4, v2
	v_cmp_ne_u32_e32 vcc, v3, v2
	s_and_saveexec_b64 s[6:7], vcc
	s_xor_b64 s[20:21], exec, s[6:7]
	s_cbranch_execz .LBB0_401
	s_waitcnt lgkmcnt(0)
	buffer_inv sc1
	v_mov_b32_e32 v0, 0x2000
	global_load_dword v0, v0, s[10:11] offset:1024 sc1
	s_add_u32 s44, s10, 0x2400
	s_addc_u32 s45, s11, 0
	s_waitcnt vmcnt(0)
	v_cmp_eq_u32_e32 vcc, v0, v1
	s_and_saveexec_b64 s[22:23], vcc
	s_cbranch_execz .LBB0_400
	s_add_u32 s42, s14, 0xff40200
	s_addc_u32 s43, s15, 0
	s_mov_b32 s6, 1
	s_mov_b64 s[46:47], 0
	v_mov_b32_e32 v0, 0
	s_branch .LBB0_391

; __device__ __forceinline__ unsigned xb_ld(unsigned* p)              { return __hip_atomic_load(p, __ATOMIC_RELAXED, __HIP_MEMORY_SCOPE_AGENT); }
; #define XB_SPIN(cond, bar) do { unsigned _sp = 0; while (cond) { __builtin_amdgcn_s_sleep(1); \
;     if ((++_sp & 255u) == 0u) { if (xb_ld(&(bar)[XB_TMO])) break; if (_sp > XB_SPIN_CAP) { atomicAdd(&(bar)[XB_TMO], 1u); break; } } } } while (0)
; __device__ __forceinline__ void xcd_barrier(const XcdBarrier& b, int wave_id) {
;     ...
;             XB_SPIN(xb_ld(&bar[XB_XGEN(b.x)]) == gen, bar);
;             __builtin_amdgcn_fence(__ATOMIC_ACQUIRE, "agent");
;             asm volatile("s_waitcnt vmcnt(0)" ::: "memory");
.LBB0_400:
	s_or_b64 exec, exec, s[22:23]
	s_waitcnt vmcnt(0)
	s_nop 0
	s_waitcnt vmcnt(0)

; __device__ __forceinline__ unsigned xb_add(unsigned* p, unsigned v) { return __hip_atomic_fetch_add(p, v, __ATOMIC_RELAXED, __HIP_MEMORY_SCOPE_AGENT); }
; __device__ __forceinline__ void xcd_barrier(const XcdBarrier& b, int wave_id) {
;     ...
;             __builtin_amdgcn_fence(__ATOMIC_ACQUIRE, "agent");
;             xb_add(&bar[XB_XGEN(b.x)], 1u);
;             asm volatile("s_waitcnt vmcnt(0)" ::: "memory");
.LBB0_418:
	s_or_b64 exec, exec, s[20:21]
	s_mov_b64 s[20:21], exec
	v_mbcnt_lo_u32_b32 v0, s20, 0
	v_mbcnt_hi_u32_b32 v0, s21, v0
	v_cmp_eq_u32_e32 vcc, 0, v0
	s_waitcnt vmcnt(0)
	buffer_inv sc1
	s_waitcnt vmcnt(0)
	s_and_saveexec_b64 s[22:23], vcc
	s_cbranch_execz .LBB0_420
	s_bcnt1_i32_b64 s6, s[20:21]
	v_mov_b32_e32 v0, 0x2000
	v_mov_b32_e32 v1, s6
	global_atomic_add v0, v1, s[10:11] offset:1024

; __device__ __forceinline__ unsigned xb_ld(unsigned* p)              { return __hip_atomic_load(p, __ATOMIC_RELAXED, __HIP_MEMORY_SCOPE_AGENT); }
; __device__ __forceinline__ unsigned xb_add(unsigned* p, unsigned v) { return __hip_atomic_fetch_add(p, v, __ATOMIC_RELAXED, __HIP_MEMORY_SCOPE_AGENT); }
; #define XB_SPIN(cond, bar) do { unsigned _sp = 0; while (cond) { __builtin_amdgcn_s_sleep(1); \
;     if ((++_sp & 255u) == 0u) { if (xb_ld(&(bar)[XB_TMO])) break; if (_sp > XB_SPIN_CAP) { atomicAdd(&(bar)[XB_TMO], 1u); break; } } } } while (0)
; __device__ __forceinline__ void xcd_barrier(const XcdBarrier& b, int wave_id) {
;     ...
;         const unsigned old = xb_add(&bar[XB_XSUB(b.x)], 1u);
;         const unsigned gen = old / nloc;
;         if (old + 1u == (gen + 1u) * nloc) {
;             __builtin_amdgcn_fence(__ATOMIC_RELEASE, "agent");
;             asm volatile("s_waitcnt vmcnt(0)" ::: "memory");
;             const unsigned og = xb_add(&bar[XB_TOP], 1u);
;             const unsigned tg = og / nx;
;             if (og + 1u == (tg + 1u) * nx) xb_add(&bar[XB_TOPGEN], 1u);
;             else XB_SPIN(xb_ld(&bar[XB_TOPGEN]) == tg, bar);
;             __builtin_amdgcn_fence(__ATOMIC_ACQUIRE, "agent");
;             xb_add(&bar[XB_XGEN(b.x)], 1u);
;             asm volatile("s_waitcnt vmcnt(0)" ::: "memory");
;         } else {
;             XB_SPIN(xb_ld(&bar[XB_XGEN(b.x)]) == gen, bar);
;             __builtin_amdgcn_fence(__ATOMIC_ACQUIRE, "agent");
;             asm volatile("s_waitcnt vmcnt(0)" ::: "memory");
;         }
.LBB0_470:
	s_or_b64 exec, exec, s[22:23]
	v_cvt_f32_u32_e32 v4, v2
	s_waitcnt vmcnt(0)
	v_readfirstlane_b32 s6, v3
	v_sub_u32_e32 v3, 0, v2
	v_rcp_iflag_f32_e32 v4, v4
	v_add_u32_e32 v5, s6, v1
	v_mul_f32_e32 v4, 0x4f7ffffe, v4
	v_cvt_u32_f32_e32 v4, v4
	v_mul_lo_u32 v1, v3, v4
	v_mul_hi_u32 v1, v4, v1
	v_add_u32_e32 v1, v4, v1
	v_mul_hi_u32 v1, v5, v1
	v_mul_lo_u32 v3, v1, v2
	v_sub_u32_e32 v3, v5, v3
	v_add_u32_e32 v4, 1, v1
	v_cmp_ge_u32_e32 vcc, v3, v2
	s_nop 1
	v_cndmask_b32_e32 v1, v1, v4, vcc
	v_sub_u32_e32 v4, v3, v2
	v_cndmask_b32_e32 v3, v3, v4, vcc
	v_add_u32_e32 v4, 1, v1
	v_cmp_ge_u32_e32 vcc, v3, v2
	v_add_u32_e32 v3, 1, v5
	s_nop 0
	v_cndmask_b32_e32 v1, v1, v4, vcc
	v_mul_lo_u32 v4, v2, v1
	v_add_u32_e32 v2, v4, v2
	v_cmp_ne_u32_e32 vcc, v3, v2
	s_and_saveexec_b64 s[6:7], vcc
	s_xor_b64 s[10:11], exec, s[6:7]
	s_cbranch_execz .LBB0_484
	s_waitcnt lgkmcnt(0)
	buffer_inv sc1
	v_mov_b32_e32 v0, 0x2000
	global_load_dword v0, v0, s[8:9] offset:1024 sc1
	s_add_u32 s40, s8, 0x2400
	s_addc_u32 s41, s9, 0
	s_waitcnt vmcnt(0)
	v_cmp_eq_u32_e32 vcc, v0, v1
	s_and_saveexec_b64 s[22:23], vcc
	s_cbranch_execz .LBB0_483
	s_add_u32 s38, s14, 0xff40200
	s_addc_u32 s39, s15, 0
	s_mov_b32 s6, 1
	s_mov_b64 s[42:43], 0
	v_mov_b32_e32 v0, 0
	s_branch .LBB0_474

; __device__ __forceinline__ unsigned xb_add(unsigned* p, unsigned v) { return __hip_atomic_fetch_add(p, v, __ATOMIC_RELAXED, __HIP_MEMORY_SCOPE_AGENT); }
; __device__ __forceinline__ void xcd_barrier(const XcdBarrier& b, int wave_id) {
;     ...
;             __builtin_amdgcn_fence(__ATOMIC_ACQUIRE, "agent");
;             xb_add(&bar[XB_XGEN(b.x)], 1u);
;             asm volatile("s_waitcnt vmcnt(0)" ::: "memory");
.LBB0_501:
	s_or_b64 exec, exec, s[10:11]
	s_mov_b64 s[10:11], exec
	v_mbcnt_lo_u32_b32 v0, s10, 0
	v_mbcnt_hi_u32_b32 v0, s11, v0
	v_cmp_eq_u32_e32 vcc, 0, v0
	s_waitcnt vmcnt(0)
	buffer_inv sc1
	s_waitcnt vmcnt(0)
	s_and_saveexec_b64 s[22:23], vcc
	s_cbranch_execz .LBB0_503
	s_bcnt1_i32_b64 s6, s[10:11]
	v_mov_b32_e32 v0, 0x2000
	v_mov_b32_e32 v1, s6
	global_atomic_add v0, v1, s[8:9] offset:1024

; __device__ __forceinline__ unsigned xb_ld(unsigned* p)              { return __hip_atomic_load(p, __ATOMIC_RELAXED, __HIP_MEMORY_SCOPE_AGENT); }
; __device__ __forceinline__ unsigned xb_add(unsigned* p, unsigned v) { return __hip_atomic_fetch_add(p, v, __ATOMIC_RELAXED, __HIP_MEMORY_SCOPE_AGENT); }
; #define XB_SPIN(cond, bar) do { unsigned _sp = 0; while (cond) { __builtin_amdgcn_s_sleep(1); \
;     if ((++_sp & 255u) == 0u) { if (xb_ld(&(bar)[XB_TMO])) break; if (_sp > XB_SPIN_CAP) { atomicAdd(&(bar)[XB_TMO], 1u); break; } } } } while (0)
; __device__ __forceinline__ void xcd_barrier(const XcdBarrier& b, int wave_id) {
;     ...
;         const unsigned old = xb_add(&bar[XB_XSUB(b.x)], 1u);
;         const unsigned gen = old / nloc;
;         if (old + 1u == (gen + 1u) * nloc) {
;             __builtin_amdgcn_fence(__ATOMIC_RELEASE, "agent");
;             asm volatile("s_waitcnt vmcnt(0)" ::: "memory");
;             const unsigned og = xb_add(&bar[XB_TOP], 1u);
;             const unsigned tg = og / nx;
;             if (og + 1u == (tg + 1u) * nx) xb_add(&bar[XB_TOPGEN], 1u);
;             else XB_SPIN(xb_ld(&bar[XB_TOPGEN]) == tg, bar);
;             __builtin_amdgcn_fence(__ATOMIC_ACQUIRE, "agent");
;             xb_add(&bar[XB_XGEN(b.x)], 1u);
;             asm volatile("s_waitcnt vmcnt(0)" ::: "memory");
;         } else {
;             XB_SPIN(xb_ld(&bar[XB_XGEN(b.x)]) == gen, bar);
;             __builtin_amdgcn_fence(__ATOMIC_ACQUIRE, "agent");
;             asm volatile("s_waitcnt vmcnt(0)" ::: "memory");
;         }
.LBB0_578:
	s_or_b64 exec, exec, s[22:23]
	v_cvt_f32_u32_e32 v4, v2
	s_waitcnt vmcnt(0)
	v_readfirstlane_b32 s8, v3
	v_sub_u32_e32 v3, 0, v2
	v_rcp_iflag_f32_e32 v4, v4
	v_add_u32_e32 v5, s8, v1
	v_mul_f32_e32 v4, 0x4f7ffffe, v4
	v_cvt_u32_f32_e32 v4, v4
	v_mul_lo_u32 v1, v3, v4
	v_mul_hi_u32 v1, v4, v1
	v_add_u32_e32 v1, v4, v1
	v_mul_hi_u32 v1, v5, v1
	v_mul_lo_u32 v3, v1, v2
	v_sub_u32_e32 v3, v5, v3
	v_add_u32_e32 v4, 1, v1
	v_cmp_ge_u32_e32 vcc, v3, v2
	s_nop 1
	v_cndmask_b32_e32 v1, v1, v4, vcc
	v_sub_u32_e32 v4, v3, v2
	v_cndmask_b32_e32 v3, v3, v4, vcc
	v_add_u32_e32 v4, 1, v1
	v_cmp_ge_u32_e32 vcc, v3, v2
	v_add_u32_e32 v3, 1, v5
	s_nop 0
	v_cndmask_b32_e32 v1, v1, v4, vcc
	v_mul_lo_u32 v4, v2, v1
	v_add_u32_e32 v2, v4, v2
	v_cmp_ne_u32_e32 vcc, v3, v2
	s_and_saveexec_b64 s[8:9], vcc
	s_xor_b64 s[8:9], exec, s[8:9]
	s_cbranch_execz .LBB0_592
	s_waitcnt lgkmcnt(0)
	buffer_inv sc1
	v_mov_b32_e32 v0, 0x2000
	global_load_dword v0, v0, s[6:7] offset:1024 sc1
	s_add_u32 s40, s6, 0x2400
	s_addc_u32 s41, s7, 0
	s_waitcnt vmcnt(0)
	v_cmp_eq_u32_e32 vcc, v0, v1
	s_and_saveexec_b64 s[22:23], vcc
	s_cbranch_execz .LBB0_591
	s_add_u32 s38, s14, 0xff40200
	s_addc_u32 s39, s15, 0
	s_mov_b32 s26, 1
	s_mov_b64 s[42:43], 0
	v_mov_b32_e32 v0, 0
	s_branch .LBB0_582

; __device__ __forceinline__ unsigned xb_add(unsigned* p, unsigned v) { return __hip_atomic_fetch_add(p, v, __ATOMIC_RELAXED, __HIP_MEMORY_SCOPE_AGENT); }
; __device__ __forceinline__ void xcd_barrier(const XcdBarrier& b, int wave_id) {
;     ...
;             __builtin_amdgcn_fence(__ATOMIC_ACQUIRE, "agent");
;             xb_add(&bar[XB_XGEN(b.x)], 1u);
;             asm volatile("s_waitcnt vmcnt(0)" ::: "memory");
.LBB0_609:
	s_or_b64 exec, exec, s[8:9]
	s_mov_b64 s[8:9], exec
	v_mbcnt_lo_u32_b32 v0, s8, 0
	v_mbcnt_hi_u32_b32 v0, s9, v0
	v_cmp_eq_u32_e32 vcc, 0, v0
	s_waitcnt vmcnt(0)
	buffer_inv sc1
	s_waitcnt vmcnt(0)
	s_and_saveexec_b64 s[22:23], vcc
	s_cbranch_execz .LBB0_611
	s_bcnt1_i32_b64 s8, s[8:9]
	v_mov_b32_e32 v0, 0x2000
	v_mov_b32_e32 v1, s8
	global_atomic_add v0, v1, s[6:7] offset:1024

; __device__ __forceinline__ unsigned xb_ld(unsigned* p)              { return __hip_atomic_load(p, __ATOMIC_RELAXED, __HIP_MEMORY_SCOPE_AGENT); }
; __device__ __forceinline__ unsigned xb_add(unsigned* p, unsigned v) { return __hip_atomic_fetch_add(p, v, __ATOMIC_RELAXED, __HIP_MEMORY_SCOPE_AGENT); }
; #define XB_SPIN(cond, bar) do { unsigned _sp = 0; while (cond) { __builtin_amdgcn_s_sleep(1); \
;     if ((++_sp & 255u) == 0u) { if (xb_ld(&(bar)[XB_TMO])) break; if (_sp > XB_SPIN_CAP) { atomicAdd(&(bar)[XB_TMO], 1u); break; } } } } while (0)
; __device__ __forceinline__ void xcd_barrier(const XcdBarrier& b, int wave_id) {
;     ...
;         const unsigned old = xb_add(&bar[XB_XSUB(b.x)], 1u);
;         const unsigned gen = old / nloc;
;         if (old + 1u == (gen + 1u) * nloc) {
;             __builtin_amdgcn_fence(__ATOMIC_RELEASE, "agent");
;             asm volatile("s_waitcnt vmcnt(0)" ::: "memory");
;             const unsigned og = xb_add(&bar[XB_TOP], 1u);
;             const unsigned tg = og / nx;
;             if (og + 1u == (tg + 1u) * nx) xb_add(&bar[XB_TOPGEN], 1u);
;             else XB_SPIN(xb_ld(&bar[XB_TOPGEN]) == tg, bar);
;             __builtin_amdgcn_fence(__ATOMIC_ACQUIRE, "agent");
;             xb_add(&bar[XB_XGEN(b.x)], 1u);
;             asm volatile("s_waitcnt vmcnt(0)" ::: "memory");
;         } else {
;             XB_SPIN(xb_ld(&bar[XB_XGEN(b.x)]) == gen, bar);
;             __builtin_amdgcn_fence(__ATOMIC_ACQUIRE, "agent");
;             asm volatile("s_waitcnt vmcnt(0)" ::: "memory");
;         }
.LBB0_674:
	s_or_b64 exec, exec, s[16:17]
	v_cvt_f32_u32_e32 v4, v2
	s_waitcnt vmcnt(0)
	v_readfirstlane_b32 s8, v3
	v_sub_u32_e32 v3, 0, v2
	v_rcp_iflag_f32_e32 v4, v4
	v_add_u32_e32 v5, s8, v1
	v_mul_f32_e32 v4, 0x4f7ffffe, v4
	v_cvt_u32_f32_e32 v4, v4
	v_mul_lo_u32 v1, v3, v4
	v_mul_hi_u32 v1, v4, v1
	v_add_u32_e32 v1, v4, v1
	v_mul_hi_u32 v1, v5, v1
	v_mul_lo_u32 v3, v1, v2
	v_sub_u32_e32 v3, v5, v3
	v_add_u32_e32 v4, 1, v1
	v_cmp_ge_u32_e32 vcc, v3, v2
	s_nop 1
	v_cndmask_b32_e32 v1, v1, v4, vcc
	v_sub_u32_e32 v4, v3, v2
	v_cndmask_b32_e32 v3, v3, v4, vcc
	v_add_u32_e32 v4, 1, v1
	v_cmp_ge_u32_e32 vcc, v3, v2
	v_add_u32_e32 v3, 1, v5
	s_nop 0
	v_cndmask_b32_e32 v1, v1, v4, vcc
	v_mul_lo_u32 v4, v2, v1
	v_add_u32_e32 v2, v4, v2
	v_cmp_ne_u32_e32 vcc, v3, v2
	s_and_saveexec_b64 s[8:9], vcc
	s_xor_b64 s[8:9], exec, s[8:9]
	s_cbranch_execz .LBB0_688
	s_waitcnt lgkmcnt(0)
	buffer_inv sc1
	v_mov_b32_e32 v0, 0x2000
	global_load_dword v0, v0, s[6:7] offset:1024 sc1
	s_add_u32 s22, s6, 0x2400
	s_addc_u32 s23, s7, 0
	s_waitcnt vmcnt(0)
	v_cmp_eq_u32_e32 vcc, v0, v1
	s_and_saveexec_b64 s[16:17], vcc
	s_cbranch_execz .LBB0_687
	s_add_u32 s20, s14, 0xff40200
	s_addc_u32 s21, s15, 0
	s_mov_b32 s26, 1
	s_mov_b64 s[36:37], 0
	v_mov_b32_e32 v0, 0
	s_branch .LBB0_678

; __device__ __forceinline__ unsigned xb_ld(unsigned* p)              { return __hip_atomic_load(p, __ATOMIC_RELAXED, __HIP_MEMORY_SCOPE_AGENT); }
; #define XB_SPIN(cond, bar) do { unsigned _sp = 0; while (cond) { __builtin_amdgcn_s_sleep(1); \
;     if ((++_sp & 255u) == 0u) { if (xb_ld(&(bar)[XB_TMO])) break; if (_sp > XB_SPIN_CAP) { atomicAdd(&(bar)[XB_TMO], 1u); break; } } } } while (0)
; __device__ __forceinline__ void xcd_barrier(const XcdBarrier& b, int wave_id) {
;     ...
;             XB_SPIN(xb_ld(&bar[XB_XGEN(b.x)]) == gen, bar);
;             __builtin_amdgcn_fence(__ATOMIC_ACQUIRE, "agent");
;             asm volatile("s_waitcnt vmcnt(0)" ::: "memory");
.LBB0_687:
	s_or_b64 exec, exec, s[16:17]
	s_waitcnt vmcnt(0)
	s_nop 0
	s_waitcnt vmcnt(0)

; __device__ __forceinline__ unsigned xb_add(unsigned* p, unsigned v) { return __hip_atomic_fetch_add(p, v, __ATOMIC_RELAXED, __HIP_MEMORY_SCOPE_AGENT); }
; __device__ __forceinline__ void xcd_barrier(const XcdBarrier& b, int wave_id) {
;     ...
;             __builtin_amdgcn_fence(__ATOMIC_ACQUIRE, "agent");
;             xb_add(&bar[XB_XGEN(b.x)], 1u);
;             asm volatile("s_waitcnt vmcnt(0)" ::: "memory");
.LBB0_705:
	s_or_b64 exec, exec, s[8:9]
	s_mov_b64 s[8:9], exec
	v_mbcnt_lo_u32_b32 v0, s8, 0
	v_mbcnt_hi_u32_b32 v0, s9, v0
	v_cmp_eq_u32_e32 vcc, 0, v0
	s_waitcnt vmcnt(0)
	buffer_inv sc1
	s_waitcnt vmcnt(0)
	s_and_saveexec_b64 s[16:17], vcc
	s_cbranch_execz .LBB0_707
	s_bcnt1_i32_b64 s8, s[8:9]
	v_mov_b32_e32 v0, 0x2000
	v_mov_b32_e32 v1, s8
	global_atomic_add v0, v1, s[6:7] offset:1024

; __device__ __forceinline__ unsigned xb_ld(unsigned* p)              { return __hip_atomic_load(p, __ATOMIC_RELAXED, __HIP_MEMORY_SCOPE_AGENT); }
; __device__ __forceinline__ unsigned xb_add(unsigned* p, unsigned v) { return __hip_atomic_fetch_add(p, v, __ATOMIC_RELAXED, __HIP_MEMORY_SCOPE_AGENT); }
; #define XB_SPIN(cond, bar) do { unsigned _sp = 0; while (cond) { __builtin_amdgcn_s_sleep(1); \
;     if ((++_sp & 255u) == 0u) { if (xb_ld(&(bar)[XB_TMO])) break; if (_sp > XB_SPIN_CAP) { atomicAdd(&(bar)[XB_TMO], 1u); break; } } } } while (0)
; __device__ __forceinline__ void xcd_barrier(const XcdBarrier& b, int wave_id) {
;     ...
;         const unsigned old = xb_add(&bar[XB_XSUB(b.x)], 1u);
;         const unsigned gen = old / nloc;
;         if (old + 1u == (gen + 1u) * nloc) {
;             __builtin_amdgcn_fence(__ATOMIC_RELEASE, "agent");
;             asm volatile("s_waitcnt vmcnt(0)" ::: "memory");
;             const unsigned og = xb_add(&bar[XB_TOP], 1u);
;             const unsigned tg = og / nx;
;             if (og + 1u == (tg + 1u) * nx) xb_add(&bar[XB_TOPGEN], 1u);
;             else XB_SPIN(xb_ld(&bar[XB_TOPGEN]) == tg, bar);
;             __builtin_amdgcn_fence(__ATOMIC_ACQUIRE, "agent");
;             xb_add(&bar[XB_XGEN(b.x)], 1u);
;             asm volatile("s_waitcnt vmcnt(0)" ::: "memory");
;         } else {
;             XB_SPIN(xb_ld(&bar[XB_XGEN(b.x)]) == gen, bar);
;             __builtin_amdgcn_fence(__ATOMIC_ACQUIRE, "agent");
;             asm volatile("s_waitcnt vmcnt(0)" ::: "memory");
;         }
.LBB0_750:
	s_or_b64 exec, exec, s[18:19]
	v_cvt_f32_u32_e32 v4, v2
	s_waitcnt vmcnt(0)
	v_readfirstlane_b32 s3, v3
	v_sub_u32_e32 v3, 0, v2
	v_rcp_iflag_f32_e32 v4, v4
	v_add_u32_e32 v5, s3, v1
	v_mul_f32_e32 v4, 0x4f7ffffe, v4
	v_cvt_u32_f32_e32 v4, v4
	v_mul_lo_u32 v1, v3, v4
	v_mul_hi_u32 v1, v4, v1
	v_add_u32_e32 v1, v4, v1
	v_mul_hi_u32 v1, v5, v1
	v_mul_lo_u32 v3, v1, v2
	v_sub_u32_e32 v3, v5, v3
	v_add_u32_e32 v4, 1, v1
	v_cmp_ge_u32_e32 vcc, v3, v2
	s_nop 1
	v_cndmask_b32_e32 v1, v1, v4, vcc
	v_sub_u32_e32 v4, v3, v2
	v_cndmask_b32_e32 v3, v3, v4, vcc
	v_add_u32_e32 v4, 1, v1
	v_cmp_ge_u32_e32 vcc, v3, v2
	v_add_u32_e32 v3, 1, v5
	s_nop 0
	v_cndmask_b32_e32 v1, v1, v4, vcc
	v_mul_lo_u32 v4, v2, v1
	v_add_u32_e32 v2, v4, v2
	v_cmp_ne_u32_e32 vcc, v3, v2
	s_and_saveexec_b64 s[16:17], vcc
	s_xor_b64 s[16:17], exec, s[16:17]
	s_cbranch_execz .LBB0_764
	s_waitcnt lgkmcnt(0)
	buffer_inv sc1
	v_mov_b32_e32 v0, 0x2000
	global_load_dword v0, v0, s[4:5] offset:1024 sc1
	s_add_u32 s22, s4, 0x2400
	s_addc_u32 s23, s5, 0
	s_waitcnt vmcnt(0)
	v_cmp_eq_u32_e32 vcc, v0, v1
	s_and_saveexec_b64 s[18:19], vcc
	s_cbranch_execz .LBB0_763
	s_add_u32 s20, s14, 0xff40200
	s_addc_u32 s21, s15, 0
	s_mov_b32 s3, 1
	s_mov_b64 s[26:27], 0
	v_mov_b32_e32 v0, 0
	s_branch .LBB0_754

; __device__ __forceinline__ unsigned xb_add(unsigned* p, unsigned v) { return __hip_atomic_fetch_add(p, v, __ATOMIC_RELAXED, __HIP_MEMORY_SCOPE_AGENT); }
; __device__ __forceinline__ void xcd_barrier(const XcdBarrier& b, int wave_id) {
;     ...
;             __builtin_amdgcn_fence(__ATOMIC_ACQUIRE, "agent");
;             xb_add(&bar[XB_XGEN(b.x)], 1u);
;             asm volatile("s_waitcnt vmcnt(0)" ::: "memory");
.LBB0_781:
	s_or_b64 exec, exec, s[14:15]
	s_mov_b64 s[14:15], exec
	v_mbcnt_lo_u32_b32 v0, s14, 0
	v_mbcnt_hi_u32_b32 v0, s15, v0
	v_cmp_eq_u32_e32 vcc, 0, v0
	s_waitcnt vmcnt(0)
	buffer_inv sc1
	s_waitcnt vmcnt(0)
	s_and_saveexec_b64 s[16:17], vcc
	s_cbranch_execz .LBB0_783
	s_bcnt1_i32_b64 s3, s[14:15]
	v_mov_b32_e32 v0, 0x2000
	v_mov_b32_e32 v1, s3
	global_atomic_add v0, v1, s[4:5] offset:1024
